# attention / GLA phases: static priority raise moved to waves 0-3 instead of waves 4-7
# baseline (speedup 1.0000x reference)
.LBB0_511:
	s_or_b64 exec, exec, s[4:5]
	s_waitcnt lgkmcnt(0)
	s_barrier
	v_readfirstlane_b32 s92, v240
	s_cmpk_lt_u32 s92, 0x100
	s_cbranch_scc0 .Lprio_a
	s_setprio 1
